# L2 warm-up prefetch of next rw_stage1 task r/k rows (dummy loads issued with the cross-task operand prefetch)
# baseline (speedup 1.0000x reference)
.LBB0_748:
	v_readlane_b32 s14, v255, 19
	s_cmpk_lt_i32 s14, 0x400
	v_readlane_b32 s44, v255, 24
	s_cselect_b64 s[18:19], -1, 0
	s_cmpk_gt_i32 s14, 0x3ff
	s_mul_hi_i32 s0, s44, 0x1a80
	s_mul_i32 s1, s44, 0x1a80
	s_mul_hi_i32 s2, s44, 0x30000
	s_mul_i32 s4, s44, 0x30000
	v_readlane_b32 s15, v255, 20
	v_readlane_b32 s45, v255, 25
	s_cbranch_scc1 .LBB0_752
	v_mov_b32_e32 v6, v235
	v_readlane_b32 s3, v255, 21
	s_andn2_b32 s3, s3, 63
	s_waitcnt lgkmcnt(0)
	v_ashrrev_i32_e32 v7, 3, v6
	v_and_b32_e32 v28, 7, v6
	v_add_u32_e32 v18, s3, v7
	s_lshl_b32 s3, s14, 6
	s_and_b32 s3, s3, 0x1c0
	v_lshlrev_b32_e32 v6, 3, v28
	v_or_b32_e32 v7, s3, v6
	v_mov_b64_e32 v[8:9], s[12:13]
	v_mad_i64_i32 v[22:23], s[14:15], v18, s9, v[8:9]
	v_lshlrev_b32_e32 v190, 1, v7
	v_lshl_add_u64 v[26:27], v[22:23], 0, v[190:191]
	v_add_co_u32_e32 v8, vcc, 0xa403000, v26
	v_mov_b32_e32 v7, v191
	s_nop 0
	v_addc_co_u32_e32 v9, vcc, 0, v27, vcc
	v_lshl_add_u64 v[6:7], v[22:23], 0, v[6:7]
	v_mul_u32_u24_e32 v10, 12, v28
	v_add_co_u32_e32 v14, vcc, 0xa403000, v6
	v_lshlrev_b32_e32 v190, 1, v10
	s_nop 0
	v_addc_co_u32_e32 v15, vcc, 0, v7, vcc
	v_lshl_add_u64 v[24:25], v[22:23], 0, v[190:191]
	v_add_co_u32_e32 v10, vcc, 0xa403000, v24
	s_mov_b64 s[14:15], 0xa4034a0
	s_nop 0
	v_addc_co_u32_e32 v11, vcc, 0, v25, vcc
	global_load_dwordx2 v[158:159], v[8:9], off offset:-2016
	global_load_dwordx2 v[158:159], v[8:9], off offset:-992
	global_load_dwordx4 v[6:9], v[8:9], off offset:32
	s_nop 0
	global_load_dwordx2 v[158:159], v[14:15], off offset:1056
	v_lshl_add_u64 v[16:17], v[24:25], 0, s[14:15]
	global_load_dwordx4 v[10:13], v[10:11], off offset:1184
	s_nop 0
	global_load_dwordx2 v[162:163], v[14:15], off offset:1120
	global_load_dwordx2 v[160:161], v[16:17], off offset:16
	v_mov_b32_e32 v190, v191
	v_cmp_lt_i32_e32 vcc, 0, v18
	v_mov_b32_e32 v14, v191
	v_mov_b32_e32 v15, v191
	v_mov_b32_e32 v16, v191
	v_mov_b32_e32 v17, v191
	v_mov_b64_e32 v[164:165], v[190:191]
	v_mov_b64_e32 v[166:167], v[190:191]
	v_mov_b64_e32 v[18:19], v[190:191]
	v_mov_b64_e32 v[20:21], v[190:191]
	v_mov_b64_e32 v[168:169], v[190:191]
	s_and_saveexec_b64 s[36:37], vcc
	v_readlane_b32 s38, v255, 26
	s_movk_i32 s5, 0x1000
	v_readlane_b32 s39, v255, 27
	s_cbranch_execz .LBB0_751
	v_lshlrev_b32_e32 v16, 2, v28
	v_add_co_u32_e32 v14, vcc, 0xa3ff000, v26
	v_lshlrev_b32_e32 v190, 1, v16
	s_nop 0
	v_addc_co_u32_e32 v15, vcc, 0, v27, vcc
	v_lshl_add_u64 v[16:17], v[22:23], 0, v[190:191]
	v_add_co_u32_e32 v22, vcc, 0xa3ff000, v16
	s_mov_b64 s[14:15], 0xa3ffea0
	s_nop 0
	v_addc_co_u32_e32 v23, vcc, 0, v17, vcc
	v_add_co_u32_e32 v18, vcc, 0xa3ff000, v24
	global_load_dwordx2 v[164:165], v[14:15], off offset:544
	global_load_dwordx2 v[164:165], v[14:15], off offset:1568
	global_load_dwordx4 v[14:17], v[14:15], off offset:2592
	s_nop 0
	global_load_dwordx2 v[164:165], v[22:23], off offset:3616
	v_addc_co_u32_e32 v19, vcc, 0, v25, vcc
	v_lshl_add_u64 v[26:27], v[24:25], 0, s[14:15]
	global_load_dwordx4 v[18:21], v[18:19], off offset:3744
	s_nop 0
	global_load_dwordx2 v[166:167], v[22:23], off offset:3680
	global_load_dwordx2 v[168:169], v[26:27], off offset:16

.LBB0_759:
	s_or_b64 exec, exec, s[4:5]
	v_add_f32_e32 v78, v78, v79
	s_add_i32 s14, s42, s22
	s_cmpk_gt_i32 s14, 0x3ff
	v_pk_mul_f32 v[80:81], v[170:171], v[78:79] op_sel_hi:[1,0]
	v_pk_mul_f32 v[84:85], v[172:173], v[78:79] op_sel_hi:[1,0]
	s_cselect_b64 s[18:19], -1, 0
	s_cmpk_lt_i32 s14, 0x400
	v_cvt_pk_bf16_f32 v80, v80, v81
	v_cvt_pk_bf16_f32 v81, v84, v85
	v_pk_mul_f32 v[84:85], v[174:175], v[78:79] op_sel_hi:[1,0]
	v_pk_mul_f32 v[78:79], v[176:177], v[78:79] op_sel_hi:[1,0]
	s_cselect_b32 s15, s14, -1
	v_cvt_pk_bf16_f32 v84, v84, v85
	v_cvt_pk_bf16_f32 v85, v78, v79
	s_ashr_i32 s43, s42, 31
	v_lshrrev_b32_e32 v77, 5, v242
	v_lshrrev_b32_e32 v78, 1, v214
	s_mov_b32 s29, 0xfffffc
	s_lshl_b64 s[4:5], s[42:43], 13
	v_and_or_b32 v77, v77, s29, v78
	v_lshlrev_b32_e32 v78, 7, v214
	v_lshlrev_b32_e32 v79, 2, v212
	s_add_u32 s36, s0, s4
	v_and_b32_e32 v78, 0x80, v78
	v_lshlrev_b32_e32 v77, 8, v77
	v_and_b32_e32 v79, 60, v79
	s_addc_u32 s37, s1, s5
	v_or3_b32 v78, v77, v79, v78
	s_add_u32 s4, s3, s4
	v_ashrrev_i32_e32 v79, 31, v78
	s_addc_u32 s5, s23, s5
	v_lshlrev_b64 v[78:79], 1, v[78:79]
	v_cvt_pk_bf16_f32 v82, v122, v123
	v_cvt_pk_bf16_f32 v83, v124, v125
	v_lshl_add_u64 v[88:89], s[36:37], 0, v[78:79]
	v_lshl_add_u64 v[78:79], s[4:5], 0, v[78:79]
	v_cvt_pk_bf16_f32 v86, v118, v119
	v_cvt_pk_bf16_f32 v87, v120, v121
	global_store_dwordx2 v[88:89], v[80:81], off
	global_store_dwordx2 v[78:79], v[82:83], off
	global_store_dwordx2 v[88:89], v[84:85], off offset:128
	global_store_dwordx2 v[78:79], v[86:87], off offset:128
	s_waitcnt lgkmcnt(0)
	s_barrier
	s_cmp_gt_i32 s15, -1
	v_mov_b32_e32 v170, v235
	s_cselect_b64 s[36:37], -1, 0
	s_cmp_lt_i32 s15, 0
	s_cbranch_scc1 .LBB0_763
	v_mov_b32_e32 v6, v235
	s_lshl_b32 s4, s15, 3
	s_and_b32 s4, s4, 0x7fffffc0
	v_ashrrev_i32_e32 v7, 3, v6
	v_and_b32_e32 v77, 7, v6
	v_add_u32_e32 v18, s4, v7
	s_lshl_b32 s4, s15, 6
	s_and_b32 s4, s4, 0x1c0
	v_lshlrev_b32_e32 v6, 3, v77
	v_or_b32_e32 v7, s4, v6
	v_mov_b64_e32 v[8:9], s[12:13]
	v_mad_i64_i32 v[78:79], s[4:5], v18, s9, v[8:9]
	v_lshlrev_b32_e32 v190, 1, v7
	v_lshl_add_u64 v[82:83], v[78:79], 0, v[190:191]
	v_add_co_u32_e32 v8, vcc, 0xa403000, v82
	v_mov_b32_e32 v7, v191
	s_nop 0
	v_addc_co_u32_e32 v9, vcc, 0, v83, vcc
	v_lshl_add_u64 v[6:7], v[78:79], 0, v[6:7]
	v_mul_u32_u24_e32 v10, 12, v77
	v_add_co_u32_e32 v14, vcc, 0xa403000, v6
	v_lshlrev_b32_e32 v190, 1, v10
	s_nop 0
	v_addc_co_u32_e32 v15, vcc, 0, v7, vcc
	v_lshl_add_u64 v[80:81], v[78:79], 0, v[190:191]
	v_add_co_u32_e32 v10, vcc, 0xa403000, v80
	s_mov_b64 s[4:5], 0xa4034a0
	s_nop 0
	v_addc_co_u32_e32 v11, vcc, 0, v81, vcc
	global_load_dwordx2 v[158:159], v[8:9], off offset:-2016
	global_load_dwordx2 v[158:159], v[8:9], off offset:-992
	global_load_dwordx4 v[6:9], v[8:9], off offset:32
	s_nop 0
	global_load_dwordx2 v[158:159], v[14:15], off offset:1056
	v_lshl_add_u64 v[16:17], v[80:81], 0, s[4:5]
	global_load_dwordx4 v[10:13], v[10:11], off offset:1184
	s_nop 0
	global_load_dwordx2 v[162:163], v[14:15], off offset:1120
	global_load_dwordx2 v[160:161], v[16:17], off offset:16
	v_mov_b32_e32 v190, v191
	v_cmp_lt_i32_e32 vcc, 0, v18
	v_mov_b32_e32 v14, v191
	v_mov_b32_e32 v15, v191
	v_mov_b32_e32 v16, v191
	v_mov_b32_e32 v17, v191
	v_mov_b64_e32 v[164:165], v[190:191]
	v_mov_b64_e32 v[166:167], v[190:191]
	v_mov_b64_e32 v[18:19], v[190:191]
	v_mov_b64_e32 v[20:21], v[190:191]
	v_mov_b64_e32 v[168:169], v[190:191]
	s_and_saveexec_b64 s[38:39], vcc
	s_cbranch_execz .LBB0_762
	v_lshlrev_b32_e32 v16, 2, v77
	v_add_co_u32_e32 v14, vcc, 0xa3ff000, v82
	v_lshlrev_b32_e32 v190, 1, v16
	s_nop 0
	v_addc_co_u32_e32 v15, vcc, 0, v83, vcc
	v_lshl_add_u64 v[16:17], v[78:79], 0, v[190:191]
	v_add_co_u32_e32 v78, vcc, 0xa3ff000, v16
	s_mov_b64 s[4:5], 0xa3ffea0
	s_nop 0
	v_addc_co_u32_e32 v79, vcc, 0, v17, vcc
	v_add_co_u32_e32 v18, vcc, 0xa3ff000, v80
	global_load_dwordx2 v[164:165], v[14:15], off offset:544
	global_load_dwordx2 v[164:165], v[14:15], off offset:1568
	global_load_dwordx4 v[14:17], v[14:15], off offset:2592
	s_nop 0
	global_load_dwordx2 v[164:165], v[78:79], off offset:3616
	v_addc_co_u32_e32 v19, vcc, 0, v81, vcc
	v_lshl_add_u64 v[82:83], v[80:81], 0, s[4:5]
	global_load_dwordx4 v[18:21], v[18:19], off offset:3744
	s_nop 0
	global_load_dwordx2 v[166:167], v[78:79], off offset:3680
	global_load_dwordx2 v[168:169], v[82:83], off offset:16
